# GEMM k-loop DMA blocks: LDS destination (M0) constants kept in borrowed SGPRs (saved in v255 lanes around the loop) instead of per-iteration VALU+readfirstlane
# speedup vs baseline: 1.0494x; 1.0022x over previous
; #define MFMA(a, b, c) __builtin_amdgcn_mfma_f32_32x32x16_bf16((a), (b), (c), 0, 0, 0)
;     ...
;     auto issue_at = [&](int mm0, int nn0, int kt, int buf) {
;       char* lb = L0 + buf * BUFB;
; #pragma unroll
;       for (int i = 0; i < 4; ++i) {
;         const int seg = wv * 4 + i, row = seg * 8 + gl_row;
;         const int c = (lane & 7) ^ ((row >> 1) & 7);
;         const u16* ap = (kt < g.split) ? g.a0 + (size_t)(mm0 + row) * g.ld0 + kt * g.ks0 : g.a1 + (size_t)(mm0 + row) * g.ld1 + (kt - g.split) * 64;
;         __builtin_amdgcn_global_load_lds((const unsigned*)(ap + c * 8), (__attribute__((address_space(3))) unsigned*)(lb + seg * 1024 + lane * 16), 16, 0, 0);
;       }
; #pragma unroll
;       for (int i = 0; i < BN / 64; ++i) {
;         const int seg = wv * (BN / 64) + i, row = seg * 8 + gl_row;
;         const int c = (lane & 7) ^ ((row >> 1) & 7);
;         __builtin_amdgcn_global_load_lds((const unsigned*)(g.W + (size_t)(nn0 + row) * g.K + kt * 64 + c * 8),
;                                          (__attribute__((address_space(3))) unsigned*)(lb + 256 * 128 + seg * 1024 + lane * 16), 16, 0, 0);
;       }
;     };
;     auto issue = [&](int kt, int buf) { issue_at(m0, n0, kt, buf); };
;     auto compute2 = [&](int buf) {
;       const char* lb = L0 + buf * BUFB;
; #pragma unroll
;       for (int ks = 0; ks < 4; ++ks) {
;         const int c = ks * 2 + hh;
;         bf16x8 wf[2], xf[MI];
; #pragma unroll
;         for (int j = 0; j < 2; ++j) { const int r = wn * 64 + j * 32 + l32; wf[j] = *(const bf16x8*)(lb + 256 * 128 + r * 128 + ((c ^ ((r >> 1) & 7)) << 4)); }
; #pragma unroll
;         for (int i = 0; i < MI; ++i) { const int r = wm * (MI * 32) + i * 32 + l32; xf[i] = *(const bf16x8*)(lb + r * 128 + ((c ^ ((r >> 1) & 7)) << 4)); }
; #pragma unroll
;         for (int i = 0; i < MI; ++i) {
;           acc[i][0] = MFMA(wf[0], xf[i], acc[i][0]);
;           acc[i][1] = MFMA(wf[1], xf[i], acc[i][1]);
;         }
;       }
;     };
.LBB0_798:
	v_writelane_b32 v255, s60, 0
	v_writelane_b32 v255, s61, 1
	v_writelane_b32 v255, s62, 2
	v_writelane_b32 v255, s63, 3
	v_writelane_b32 v255, s64, 4
	v_add_u32_e32 v0, v168, v169
	v_add_u32_e32 v178, v160, v169
	v_add_u32_e32 v199, v162, v169
	v_add_u32_e32 v254, v166, v169
	s_nop 0
	v_readfirstlane_b32 s60, v0
	v_readfirstlane_b32 s61, v178
	v_readfirstlane_b32 s62, v199
	v_readfirstlane_b32 s63, v254
	s_and_b32 s14, s11, 0x10000
	s_xor_b32 s15, s14, 0x10000
	s_add_i32 s15, s15, 0
	s_add_i32 s14, s14, 0
	v_add_u32_e32 v0, s14, v175
	v_add_u32_e32 v176, v0, v171
	v_add_u32_e32 v0, v0, v170
	ds_read_b128 v[200:203], v176 offset:32768
	ds_read_b128 v[204:207], v176 offset:36864
	ds_read_b128 v[208:211], v0
	ds_read_b128 v[212:215], v0 offset:4096
	ds_read_b128 v[216:219], v0 offset:8192
	ds_read_b128 v[220:223], v0 offset:12288
	s_add_i32 s64, s15, 0x8000
	s_add_i32 m0, s15, s60
	v_lshl_add_u64 v[176:177], v[152:153], 0, s[2:3]
	global_load_lds_dwordx4 v[176:177], off
	s_add_i32 m0, s15, s61
	v_lshl_add_u64 v[176:177], v[150:151], 0, s[2:3]
	global_load_lds_dwordx4 v[176:177], off
	s_add_i32 m0, s15, s62
	v_lshl_add_u64 v[176:177], v[148:149], 0, s[2:3]
	global_load_lds_dwordx4 v[176:177], off
	s_add_i32 m0, s15, s63
	v_lshl_add_u64 v[176:177], v[146:147], 0, s[2:3]
	global_load_lds_dwordx4 v[176:177], off
	s_add_i32 m0, s64, s60
	v_lshl_add_u64 v[176:177], v[144:145], 0, s[2:3]
	global_load_lds_dwordx4 v[176:177], off
	s_add_i32 m0, s64, s61
	v_lshl_add_u64 v[176:177], v[142:143], 0, s[2:3]
	global_load_lds_dwordx4 v[176:177], off
	s_add_i32 m0, s64, s62
	v_lshl_add_u64 v[176:177], v[140:141], 0, s[2:3]
	global_load_lds_dwordx4 v[176:177], off
	s_add_i32 m0, s64, s63
	v_lshl_add_u64 v[176:177], v[138:139], 0, s[2:3]
	global_load_lds_dwordx4 v[176:177], off
.Lgemm_rot_798:
	v_add_u32_e32 v0, s14, v174
	v_add_u32_e32 v176, v0, v171
	v_add_u32_e32 v0, v0, v170
	s_waitcnt lgkmcnt(3)
	v_mfma_f32_32x32x16_bf16 v[114:129], v[200:203], v[208:211], v[114:129]
	s_add_i32 s11, s11, 0x10000
	s_add_u32 s2, s2, 0x80
	s_addc_u32 s3, s3, 0
	s_cmpk_eq_i32 s2, 0x780
	ds_read_b128 v[224:227], v176 offset:32768
	v_mfma_f32_32x32x16_bf16 v[98:113], v[204:207], v[208:211], v[98:113]
	ds_read_b128 v[228:231], v176 offset:36864
	s_waitcnt lgkmcnt(4)
	v_mfma_f32_32x32x16_bf16 v[82:97], v[200:203], v[212:215], v[82:97]
	ds_read_b128 v[232:235], v0
	v_mfma_f32_32x32x16_bf16 v[66:81], v[204:207], v[212:215], v[66:81]
	ds_read_b128 v[240:243], v0 offset:4096
	s_waitcnt lgkmcnt(5)
	v_mfma_f32_32x32x16_bf16 v[50:65], v[200:203], v[216:219], v[50:65]
	ds_read_b128 v[244:247], v0 offset:8192
	v_mfma_f32_32x32x16_bf16 v[34:49], v[204:207], v[216:219], v[34:49]
	ds_read_b128 v[248:251], v0 offset:12288
	s_waitcnt lgkmcnt(6)
	v_mfma_f32_32x32x16_bf16 v[18:33], v[200:203], v[220:223], v[18:33]
	v_mfma_f32_32x32x16_bf16 v[2:17], v[204:207], v[220:223], v[2:17]
	v_add_u32_e32 v0, s14, v173
	v_add_u32_e32 v176, v0, v171
	v_add_u32_e32 v0, v0, v170
	s_waitcnt lgkmcnt(3)
	v_mfma_f32_32x32x16_bf16 v[114:129], v[224:227], v[232:235], v[114:129]
	ds_read_b128 v[200:203], v176 offset:32768
	v_mfma_f32_32x32x16_bf16 v[98:113], v[228:231], v[232:235], v[98:113]
	ds_read_b128 v[204:207], v176 offset:36864
	s_waitcnt lgkmcnt(4)
	v_mfma_f32_32x32x16_bf16 v[82:97], v[224:227], v[240:243], v[82:97]
	ds_read_b128 v[208:211], v0
	v_mfma_f32_32x32x16_bf16 v[66:81], v[228:231], v[240:243], v[66:81]
	ds_read_b128 v[212:215], v0 offset:4096
	s_waitcnt lgkmcnt(5)
	v_mfma_f32_32x32x16_bf16 v[50:65], v[224:227], v[244:247], v[50:65]
	ds_read_b128 v[216:219], v0 offset:8192
	v_mfma_f32_32x32x16_bf16 v[34:49], v[228:231], v[244:247], v[34:49]
	ds_read_b128 v[220:223], v0 offset:12288
	s_waitcnt lgkmcnt(6)
	v_mfma_f32_32x32x16_bf16 v[18:33], v[224:227], v[248:251], v[18:33]
	v_mfma_f32_32x32x16_bf16 v[2:17], v[228:231], v[248:251], v[2:17]
	v_add_u32_e32 v0, s14, v172
	v_add_u32_e32 v176, v0, v171
	v_add_u32_e32 v0, v0, v170
	s_waitcnt lgkmcnt(3)
	v_mfma_f32_32x32x16_bf16 v[114:129], v[200:203], v[208:211], v[114:129]
	ds_read_b128 v[224:227], v176 offset:32768
	v_mfma_f32_32x32x16_bf16 v[98:113], v[204:207], v[208:211], v[98:113]
	ds_read_b128 v[228:231], v176 offset:36864
	s_waitcnt lgkmcnt(4)
	v_mfma_f32_32x32x16_bf16 v[82:97], v[200:203], v[212:215], v[82:97]
	ds_read_b128 v[232:235], v0
	v_mfma_f32_32x32x16_bf16 v[66:81], v[204:207], v[212:215], v[66:81]
	ds_read_b128 v[240:243], v0 offset:4096
	s_waitcnt lgkmcnt(5)
	v_mfma_f32_32x32x16_bf16 v[50:65], v[200:203], v[216:219], v[50:65]
	ds_read_b128 v[244:247], v0 offset:8192
	v_mfma_f32_32x32x16_bf16 v[34:49], v[204:207], v[216:219], v[34:49]
	ds_read_b128 v[248:251], v0 offset:12288
	s_waitcnt lgkmcnt(6)
	v_mfma_f32_32x32x16_bf16 v[18:33], v[200:203], v[220:223], v[18:33]
	v_mfma_f32_32x32x16_bf16 v[2:17], v[204:207], v[220:223], v[2:17]
	s_waitcnt vmcnt(0)
	s_waitcnt vmcnt(0) lgkmcnt(0)
	s_barrier
	s_cbranch_scc1 .Lgemm_exit_798
	s_and_b32 s14, s11, 0x10000
	s_xor_b32 s15, s14, 0x10000
	s_add_i32 s15, s15, 0
	s_add_i32 s14, s14, 0
	v_add_u32_e32 v0, s14, v175
	v_add_u32_e32 v176, v0, v171
	v_add_u32_e32 v0, v0, v170
	ds_read_b128 v[200:203], v176 offset:32768
	ds_read_b128 v[204:207], v176 offset:36864
	ds_read_b128 v[208:211], v0
	ds_read_b128 v[212:215], v0 offset:4096
	ds_read_b128 v[216:219], v0 offset:8192
	ds_read_b128 v[220:223], v0 offset:12288
	v_mfma_f32_32x32x16_bf16 v[114:129], v[224:227], v[232:235], v[114:129]
	s_add_i32 s64, s15, 0x8000
	s_add_i32 m0, s15, s60
	v_lshl_add_u64 v[176:177], v[152:153], 0, s[2:3]
	global_load_lds_dwordx4 v[176:177], off
	v_mfma_f32_32x32x16_bf16 v[98:113], v[228:231], v[232:235], v[98:113]
	s_add_i32 m0, s15, s61
	v_lshl_add_u64 v[176:177], v[150:151], 0, s[2:3]
	global_load_lds_dwordx4 v[176:177], off
	s_add_i32 m0, s15, s62
	v_mfma_f32_32x32x16_bf16 v[82:97], v[224:227], v[240:243], v[82:97]
	v_lshl_add_u64 v[176:177], v[148:149], 0, s[2:3]
	global_load_lds_dwordx4 v[176:177], off
	s_add_i32 m0, s15, s63
	v_lshl_add_u64 v[176:177], v[146:147], 0, s[2:3]
	v_mfma_f32_32x32x16_bf16 v[66:81], v[228:231], v[240:243], v[66:81]
	global_load_lds_dwordx4 v[176:177], off
	s_add_i32 m0, s64, s60
	v_lshl_add_u64 v[176:177], v[144:145], 0, s[2:3]
	global_load_lds_dwordx4 v[176:177], off
	v_mfma_f32_32x32x16_bf16 v[50:65], v[224:227], v[244:247], v[50:65]
	s_add_i32 m0, s64, s61
	v_lshl_add_u64 v[176:177], v[142:143], 0, s[2:3]
	global_load_lds_dwordx4 v[176:177], off
	s_add_i32 m0, s64, s62
	v_mfma_f32_32x32x16_bf16 v[34:49], v[228:231], v[244:247], v[34:49]
	v_lshl_add_u64 v[176:177], v[140:141], 0, s[2:3]
	global_load_lds_dwordx4 v[176:177], off
	s_add_i32 m0, s64, s63
	v_lshl_add_u64 v[176:177], v[138:139], 0, s[2:3]
	v_mfma_f32_32x32x16_bf16 v[18:33], v[224:227], v[248:251], v[18:33]
	global_load_lds_dwordx4 v[176:177], off
	v_mfma_f32_32x32x16_bf16 v[2:17], v[228:231], v[248:251], v[2:17]
	s_branch .Lgemm_rot_798
;     ...
;     auto issue_at = [&](int mm0, int nn0, int kt, int buf) {
;       char* lb = L0 + buf * BUFB;
; #pragma unroll
;       for (int i = 0; i < 4; ++i) {
;         const int seg = wv * 4 + i, row = seg * 8 + gl_row;
;         const int c = (lane & 7) ^ ((row >> 1) & 7);
;         const u16* ap = (kt < g.split) ? g.a0 + (size_t)(mm0 + row) * g.ld0 + kt * g.ks0 : g.a1 + (size_t)(mm0 + row) * g.ld1 + (kt - g.split) * 64;
;         __builtin_amdgcn_global_load_lds((const unsigned*)(ap + c * 8), (__attribute__((address_space(3))) unsigned*)(lb + seg * 1024 + lane * 16), 16, 0, 0);
;       }
; #pragma unroll
;       for (int i = 0; i < BN / 64; ++i) {
;         const int seg = wv * (BN / 64) + i, row = seg * 8 + gl_row;
;         const int c = (lane & 7) ^ ((row >> 1) & 7);
;         __builtin_amdgcn_global_load_lds((const unsigned*)(g.W + (size_t)(nn0 + row) * g.K + kt * 64 + c * 8),
;                                          (__attribute__((address_space(3))) unsigned*)(lb + 256 * 128 + seg * 1024 + lane * 16), 16, 0, 0);
;       }
;     };
; template <int MODE, int EPI, int BN>
; DI void gemm_phase(CP p, const GArgs& g, int NT, char* smem) {
;     ...
;   for (int e = j; e < total; e += nj) {
;     const int grp = e / (8 * NT);
;     const int rem = e - grp * 8 * NT;
;     const int e2 = e + nj;
;     const bool has_next = can_chain && e2 < total;
;     const int grp2 = e2 / (8 * NT), rem2 = e2 - grp2 * 8 * NT;
;     const int chain = can_chain ? ((first ? 0 : 1) | (has_next ? 2 : 0)) : 0;
;     gemm_tile<MODE, EPI, BN>(p, g, x + 8 * (grp * 8 + (rem & 7)), rem >> 3, smem, chain, x + 8 * (grp2 * 8 + (rem2 & 7)), rem2 >> 3);
;     first = false;
;   }
.Lgemm_exit_798:
	v_readlane_b32 s60, v255, 0
	v_readlane_b32 s61, v255, 1
	v_readlane_b32 s62, v255, 2
	v_readlane_b32 s63, v255, 3
	v_readlane_b32 s64, v255, 4
	v_mfma_f32_32x32x16_bf16 v[114:129], v[224:227], v[232:235], v[114:129]
	v_mfma_f32_32x32x16_bf16 v[98:113], v[228:231], v[232:235], v[98:113]
	v_mfma_f32_32x32x16_bf16 v[82:97], v[224:227], v[240:243], v[82:97]
	v_mfma_f32_32x32x16_bf16 v[66:81], v[228:231], v[240:243], v[66:81]
	v_mfma_f32_32x32x16_bf16 v[50:65], v[224:227], v[244:247], v[50:65]
	v_mfma_f32_32x32x16_bf16 v[34:49], v[228:231], v[244:247], v[34:49]
	v_mfma_f32_32x32x16_bf16 v[18:33], v[224:227], v[248:251], v[18:33]
	v_mfma_f32_32x32x16_bf16 v[2:17], v[228:231], v[248:251], v[2:17]
	s_add_i32 s95, s95, s76
	s_cmpk_gt_u32 s95, 0x9f
	s_cselect_b64 s[92:93], -1, 0
	s_and_b64 vcc, exec, s[92:93]
	s_cbranch_vccnz .LBB0_801
	s_mul_hi_u32 s2, s95, 0xcccccccd
	s_lshr_b32 s3, s2, 6
	s_mulk_i32 s3, 0xffb0
	s_lshl_b32 s11, s95, 3
	s_add_i32 s3, s3, s95
	s_and_b32 s2, s2, 0xffffc0
	s_and_b32 s11, s11, 56
	s_or_b32 s2, s2, s11
	v_readlane_b32 s11, v252, 38
	s_lshl_b32 s3, s3, 5
	s_or_b32 s2, s2, s11
	s_and_b32 s3, s3, 0xffffff00
	s_lshl_b32 s2, s2, 8
	v_add_u32_e32 v148, s3, v161
	v_add_u32_e32 v138, s2, v157
	v_ashrrev_i32_e32 v149, 31, v148
	v_ashrrev_i32_e32 v139, 31, v138
	v_lshl_add_u64 v[176:177], s[68:69], 0, v[136:137]
	v_lshl_add_u64 v[136:137], s[70:71], 0, v[136:137]
	v_lshlrev_b64 v[148:149], 11, v[148:149]
	v_add3_u32 v0, 0, v168, v169
	v_add_u32_e32 v140, s2, v161
	v_add_u32_e32 v142, s2, v165
	v_add_u32_e32 v144, s2, v167
	v_lshlrev_b64 v[138:139], 11, v[138:139]
	v_lshl_add_u64 v[136:137], v[136:137], 0, v[148:149]
	v_lshl_add_u64 v[148:149], s[70:71], 0, v[134:135]
	v_lshl_add_u64 v[134:135], s[68:69], 0, v[134:135]
	v_readfirstlane_b32 s2, v0
	v_lshl_add_u64 v[134:135], v[134:135], 0, v[138:139]
	s_mov_b32 m0, s2
	v_ashrrev_i32_e32 v141, 31, v140
	global_load_lds_dwordx4 v[134:135], off
	v_add3_u32 v134, 0, v160, v169
	v_ashrrev_i32_e32 v143, 31, v142
	v_lshlrev_b64 v[140:141], 11, v[140:141]
	v_readfirstlane_b32 s2, v134
	v_add3_u32 v135, 0, v162, v169
	v_lshlrev_b64 v[142:143], 11, v[142:143]
	v_lshl_add_u64 v[202:203], s[70:71], 0, v[132:133]
	v_lshl_add_u64 v[132:133], s[68:69], 0, v[132:133]
	v_lshl_add_u64 v[140:141], v[176:177], 0, v[140:141]
	s_mov_b32 m0, s2
	v_readfirstlane_b32 s2, v135
	v_lshl_add_u64 v[132:133], v[132:133], 0, v[142:143]
	global_load_lds_dwordx4 v[140:141], off
	s_mov_b32 m0, s2
	v_ashrrev_i32_e32 v145, 31, v144
	v_add_u32_e32 v146, s3, v157
	global_load_lds_dwordx4 v[132:133], off
	v_add3_u32 v132, 0, v166, v169
	v_ashrrev_i32_e32 v147, 31, v146
	v_lshl_add_u64 v[200:201], s[68:69], 0, v[130:131]
	v_lshlrev_b64 v[144:145], 11, v[144:145]
	v_readfirstlane_b32 s2, v132
	v_add_u32_e32 v0, 0x8000, v0
	v_add_u32_e32 v150, s3, v165
	v_add_u32_e32 v152, s3, v167
	v_lshlrev_b64 v[146:147], 11, v[146:147]
	v_lshl_add_u64 v[144:145], v[200:201], 0, v[144:145]
	s_mov_b32 m0, s2
	v_readfirstlane_b32 s2, v0
	v_add_u32_e32 v0, 0x8000, v134
	v_ashrrev_i32_e32 v151, 31, v150
	v_ashrrev_i32_e32 v153, 31, v152
	v_lshl_add_u64 v[146:147], v[148:149], 0, v[146:147]
	global_load_lds_dwordx4 v[144:145], off
	s_mov_b32 m0, s2
	v_readfirstlane_b32 s2, v0
	v_add_u32_e32 v0, 0x8000, v135
	v_lshlrev_b64 v[150:151], 11, v[150:151]
	v_lshlrev_b64 v[152:153], 11, v[152:153]
	global_load_lds_dwordx4 v[146:147], off
	s_mov_b32 m0, s2
	v_readfirstlane_b32 s2, v0
	v_add_u32_e32 v0, 0x8000, v132
	v_lshl_add_u64 v[152:153], s[70:71], 0, v[152:153]
	v_lshl_add_u64 v[150:151], v[202:203], 0, v[150:151]
	global_load_lds_dwordx4 v[136:137], off
	s_mov_b32 m0, s2
	v_readfirstlane_b32 s2, v0
	global_load_lds_dwordx4 v[150:151], off
	v_lshl_add_u64 v[130:131], v[152:153], 0, v[130:131]
	s_mov_b32 m0, s2
	s_nop 0
	global_load_lds_dwordx4 v[130:131], off

; #define MFMA(a, b, c) __builtin_amdgcn_mfma_f32_32x32x16_bf16((a), (b), (c), 0, 0, 0)
;     ...
;     auto issue_at = [&](int mm0, int nn0, int kt, int buf) {
;       char* lb = L0 + buf * BUFB;
; #pragma unroll
;       for (int i = 0; i < 4; ++i) {
;         const int seg = wv * 4 + i, row = seg * 8 + gl_row;
;         const int c = (lane & 7) ^ ((row >> 1) & 7);
;         const u16* ap = (kt < g.split) ? g.a0 + (size_t)(mm0 + row) * g.ld0 + kt * g.ks0 : g.a1 + (size_t)(mm0 + row) * g.ld1 + (kt - g.split) * 64;
;         __builtin_amdgcn_global_load_lds((const unsigned*)(ap + c * 8), (__attribute__((address_space(3))) unsigned*)(lb + seg * 1024 + lane * 16), 16, 0, 0);
;       }
; #pragma unroll
;       for (int i = 0; i < BN / 64; ++i) {
;         const int seg = wv * (BN / 64) + i, row = seg * 8 + gl_row;
;         const int c = (lane & 7) ^ ((row >> 1) & 7);
;         __builtin_amdgcn_global_load_lds((const unsigned*)(g.W + (size_t)(nn0 + row) * g.K + kt * 64 + c * 8),
;                                          (__attribute__((address_space(3))) unsigned*)(lb + 256 * 128 + seg * 1024 + lane * 16), 16, 0, 0);
;       }
;     };
;     auto issue = [&](int kt, int buf) { issue_at(m0, n0, kt, buf); };
;     auto compute2 = [&](int buf) {
;       const char* lb = L0 + buf * BUFB;
; #pragma unroll
;       for (int ks = 0; ks < 4; ++ks) {
;         const int c = ks * 2 + hh;
;         bf16x8 wf[2], xf[MI];
; #pragma unroll
;         for (int j = 0; j < 2; ++j) { const int r = wn * 64 + j * 32 + l32; wf[j] = *(const bf16x8*)(lb + 256 * 128 + r * 128 + ((c ^ ((r >> 1) & 7)) << 4)); }
; #pragma unroll
;         for (int i = 0; i < MI; ++i) { const int r = wm * (MI * 32) + i * 32 + l32; xf[i] = *(const bf16x8*)(lb + r * 128 + ((c ^ ((r >> 1) & 7)) << 4)); }
; #pragma unroll
;         for (int i = 0; i < MI; ++i) {
;           acc[i][0] = MFMA(wf[0], xf[i], acc[i][0]);
;           acc[i][1] = MFMA(wf[1], xf[i], acc[i][1]);
;         }
;       }
;     };
.LBB0_1274:
	v_writelane_b32 v255, s62, 0
	v_writelane_b32 v255, s63, 1
	v_writelane_b32 v255, s64, 2
	v_writelane_b32 v255, s65, 3
	v_writelane_b32 v255, s66, 4
	v_add_u32_e32 v228, v177, v178
	v_add_u32_e32 v229, v169, v178
	v_add_u32_e32 v230, v170, v178
	v_add_u32_e32 v231, v172, v178
	s_nop 0
	v_readfirstlane_b32 s62, v228
	v_readfirstlane_b32 s63, v229
	v_readfirstlane_b32 s64, v230
	v_readfirstlane_b32 s65, v231
	s_and_b32 s59, s56, 0x10000
	s_xor_b32 s60, s59, 0x10000
	s_add_i32 s57, s58, 1
	s_add_i32 s60, s60, 0
	s_cmp_lt_u32 s58, 21
	s_cselect_b64 vcc, -1, 0
	v_add_u32_e32 v233, s59, v201
	v_add_u32_e32 v230, v233, v175
	v_add_u32_e32 v234, v233, v174
	ds_read_b128 v[202:205], v230 offset:32768
	ds_read_b128 v[206:209], v230 offset:36864
	ds_read_b128 v[210:213], v234
	ds_read_b128 v[214:217], v234 offset:4096
	ds_read_b128 v[218:221], v234 offset:8192
	ds_read_b128 v[222:225], v234 offset:12288
	s_add_i32 s66, s60, 0x8000
	v_lshl_add_u64 v[226:227], v[160:161], 0, s[2:3]
	v_lshl_add_u64 v[228:229], v[144:145], 0, s[2:3]
	v_cndmask_b32_e32 v227, v229, v227, vcc
	v_cndmask_b32_e32 v226, v228, v226, vcc
	v_lshl_add_u64 v[226:227], v[0:1], 1, v[226:227]
	s_add_i32 m0, s60, s62
	v_lshl_add_u64 v[228:229], v[142:143], 0, s[2:3]
	global_load_lds_dwordx4 v[226:227], off
	v_lshl_add_u64 v[226:227], v[158:159], 0, s[2:3]
	v_cndmask_b32_e32 v227, v229, v227, vcc
	v_cndmask_b32_e32 v226, v228, v226, vcc
	v_lshl_add_u64 v[226:227], v[130:131], 1, v[226:227]
	s_add_i32 m0, s60, s63
	v_lshl_add_u64 v[228:229], v[140:141], 0, s[2:3]
	global_load_lds_dwordx4 v[226:227], off
	v_lshl_add_u64 v[226:227], v[156:157], 0, s[2:3]
	v_cndmask_b32_e32 v227, v229, v227, vcc
	v_cndmask_b32_e32 v226, v228, v226, vcc
	v_lshl_add_u64 v[226:227], v[132:133], 1, v[226:227]
	s_add_i32 m0, s60, s64
	v_lshl_add_u64 v[228:229], v[138:139], 0, s[2:3]
	global_load_lds_dwordx4 v[226:227], off
	v_lshl_add_u64 v[226:227], v[154:155], 0, s[2:3]
	v_cndmask_b32_e32 v226, v228, v226, vcc
	v_cndmask_b32_e32 v227, v229, v227, vcc
	s_add_i32 m0, s60, s65
	v_lshl_add_u64 v[226:227], v[134:135], 1, v[226:227]
	global_load_lds_dwordx4 v[226:227], off
	s_add_i32 m0, s66, s62
	v_lshl_add_u64 v[226:227], v[146:147], 0, s[2:3]
	global_load_lds_dwordx4 v[226:227], off
	s_add_i32 m0, s66, s63
	v_lshl_add_u64 v[226:227], v[148:149], 0, s[2:3]
	global_load_lds_dwordx4 v[226:227], off
	s_add_i32 m0, s66, s64
	v_lshl_add_u64 v[226:227], v[150:151], 0, s[2:3]
	global_load_lds_dwordx4 v[226:227], off
	v_lshl_add_u64 v[226:227], v[152:153], 0, s[2:3]
	s_add_i32 m0, s66, s65
	s_add_i32 s58, s59, 0
	global_load_lds_dwordx4 v[226:227], off
.Lgemm_rot_1274:
	v_add_u32_e32 v233, s59, v200
	v_add_u32_e32 v230, v233, v175
	v_add_u32_e32 v234, v233, v174
	s_waitcnt lgkmcnt(3)
	v_mfma_f32_32x32x16_bf16 v[114:129], v[202:205], v[210:213], v[114:129]
	s_add_u32 s2, s2, 0x80
	s_addc_u32 s3, s3, 0
	s_add_i32 s56, s56, 0x10000
	s_cmpk_eq_i32 s2, 0x1580
	s_mov_b32 s58, s57
	ds_read_b128 v[240:243], v230 offset:32768
	v_mfma_f32_32x32x16_bf16 v[98:113], v[206:209], v[210:213], v[98:113]
	ds_read_b128 v[244:247], v230 offset:36864
	s_waitcnt lgkmcnt(4)
	v_mfma_f32_32x32x16_bf16 v[82:97], v[202:205], v[214:217], v[82:97]
	ds_read_b128 v[248:251], v234
	v_mfma_f32_32x32x16_bf16 v[66:81], v[206:209], v[214:217], v[66:81]
	ds_read_b128 v[214:217], v234 offset:4096
	s_waitcnt lgkmcnt(5)
	v_mfma_f32_32x32x16_bf16 v[50:65], v[202:205], v[218:221], v[50:65]
	v_mfma_f32_32x32x16_bf16 v[34:49], v[206:209], v[218:221], v[34:49]
	ds_read_b128 v[218:221], v234 offset:8192
	s_waitcnt lgkmcnt(5)
	v_mfma_f32_32x32x16_bf16 v[18:33], v[202:205], v[222:225], v[18:33]
	v_mfma_f32_32x32x16_bf16 v[2:17], v[206:209], v[222:225], v[2:17]
	ds_read_b128 v[222:225], v234 offset:12288
	v_add_u32_e32 v233, s59, v199
	v_add_u32_e32 v230, v233, v175
	v_add_u32_e32 v234, v233, v174
	s_waitcnt lgkmcnt(3)
	v_mfma_f32_32x32x16_bf16 v[114:129], v[240:243], v[248:251], v[114:129]
	ds_read_b128 v[202:205], v230 offset:32768
	v_mfma_f32_32x32x16_bf16 v[98:113], v[244:247], v[248:251], v[98:113]
	ds_read_b128 v[206:209], v230 offset:36864
	s_waitcnt lgkmcnt(4)
	v_mfma_f32_32x32x16_bf16 v[82:97], v[240:243], v[214:217], v[82:97]
	ds_read_b128 v[210:213], v234
	v_mfma_f32_32x32x16_bf16 v[66:81], v[244:247], v[214:217], v[66:81]
	ds_read_b128 v[214:217], v234 offset:4096
	s_waitcnt lgkmcnt(5)
	v_mfma_f32_32x32x16_bf16 v[50:65], v[240:243], v[218:221], v[50:65]
	v_mfma_f32_32x32x16_bf16 v[34:49], v[244:247], v[218:221], v[34:49]
	ds_read_b128 v[218:221], v234 offset:8192
	s_waitcnt lgkmcnt(5)
	v_mfma_f32_32x32x16_bf16 v[18:33], v[240:243], v[222:225], v[18:33]
	v_mfma_f32_32x32x16_bf16 v[2:17], v[244:247], v[222:225], v[2:17]
	ds_read_b128 v[222:225], v234 offset:12288
	v_add_u32_e32 v233, s59, v176
	v_add_u32_e32 v230, v233, v175
	v_add_u32_e32 v234, v233, v174
	s_waitcnt lgkmcnt(3)
	v_mfma_f32_32x32x16_bf16 v[114:129], v[202:205], v[210:213], v[114:129]
	ds_read_b128 v[240:243], v230 offset:32768
	v_mfma_f32_32x32x16_bf16 v[98:113], v[206:209], v[210:213], v[98:113]
	ds_read_b128 v[244:247], v230 offset:36864
	s_waitcnt lgkmcnt(4)
	v_mfma_f32_32x32x16_bf16 v[82:97], v[202:205], v[214:217], v[82:97]
	ds_read_b128 v[248:251], v234
	v_mfma_f32_32x32x16_bf16 v[66:81], v[206:209], v[214:217], v[66:81]
	ds_read_b128 v[214:217], v234 offset:4096
	s_waitcnt lgkmcnt(5)
	v_mfma_f32_32x32x16_bf16 v[50:65], v[202:205], v[218:221], v[50:65]
	v_mfma_f32_32x32x16_bf16 v[34:49], v[206:209], v[218:221], v[34:49]
	ds_read_b128 v[218:221], v234 offset:8192
	s_waitcnt lgkmcnt(5)
	v_mfma_f32_32x32x16_bf16 v[18:33], v[202:205], v[222:225], v[18:33]
	v_mfma_f32_32x32x16_bf16 v[2:17], v[206:209], v[222:225], v[2:17]
	ds_read_b128 v[222:225], v234 offset:12288
	s_waitcnt vmcnt(0)
	s_waitcnt vmcnt(0) lgkmcnt(0)
	s_barrier
;     ...
;     auto issue_at = [&](int mm0, int nn0, int kt, int buf) {
;       char* lb = L0 + buf * BUFB;
; #pragma unroll
;       for (int i = 0; i < 4; ++i) {
;         const int seg = wv * 4 + i, row = seg * 8 + gl_row;
;         const int c = (lane & 7) ^ ((row >> 1) & 7);
;         const u16* ap = (kt < g.split) ? g.a0 + (size_t)(mm0 + row) * g.ld0 + kt * g.ks0 : g.a1 + (size_t)(mm0 + row) * g.ld1 + (kt - g.split) * 64;
;         __builtin_amdgcn_global_load_lds((const unsigned*)(ap + c * 8), (__attribute__((address_space(3))) unsigned*)(lb + seg * 1024 + lane * 16), 16, 0, 0);
;       }
; #pragma unroll
;       for (int i = 0; i < BN / 64; ++i) {
;         const int seg = wv * (BN / 64) + i, row = seg * 8 + gl_row;
;         const int c = (lane & 7) ^ ((row >> 1) & 7);
;         __builtin_amdgcn_global_load_lds((const unsigned*)(g.W + (size_t)(nn0 + row) * g.K + kt * 64 + c * 8),
;                                          (__attribute__((address_space(3))) unsigned*)(lb + 256 * 128 + seg * 1024 + lane * 16), 16, 0, 0);
;       }
;     };
;     auto issue = [&](int kt, int buf) { issue_at(m0, n0, kt, buf); };
;     auto compute2 = [&](int buf) {
;       const char* lb = L0 + buf * BUFB;
; #pragma unroll
;       for (int ks = 0; ks < 4; ++ks) {
;         const int c = ks * 2 + hh;
;         bf16x8 wf[2], xf[MI];
; #pragma unroll
;         for (int j = 0; j < 2; ++j) { const int r = wn * 64 + j * 32 + l32; wf[j] = *(const bf16x8*)(lb + 256 * 128 + r * 128 + ((c ^ ((r >> 1) & 7)) << 4)); }
; #pragma unroll
;         for (int i = 0; i < MI; ++i) { const int r = wm * (MI * 32) + i * 32 + l32; xf[i] = *(const bf16x8*)(lb + r * 128 + ((c ^ ((r >> 1) & 7)) << 4)); }
; #pragma unroll
;         for (int i = 0; i < MI; ++i) {
;           acc[i][0] = MFMA(wf[0], xf[i], acc[i][0]);
;           acc[i][1] = MFMA(wf[1], xf[i], acc[i][1]);
;         }
;       }
;     };
; template <int MODE, int EPI, int BN>
; DI void gemm_phase(CP p, const GArgs& g, int NT, char* smem) {
;     ...
;   for (int e = j; e < total; e += nj) {
;     const int grp = e / (8 * NT);
;     const int rem = e - grp * 8 * NT;
;     const int e2 = e + nj;
;     const bool has_next = can_chain && e2 < total;
;     const int grp2 = e2 / (8 * NT), rem2 = e2 - grp2 * 8 * NT;
;     const int chain = can_chain ? ((first ? 0 : 1) | (has_next ? 2 : 0)) : 0;
	s_cbranch_scc1 .Lgemm_exit_1274
	s_and_b32 s59, s56, 0x10000
	s_xor_b32 s60, s59, 0x10000
	s_add_i32 s57, s58, 1
	s_add_i32 s60, s60, 0
	s_cmp_lt_u32 s58, 21
	s_cselect_b64 vcc, -1, 0
	v_add_u32_e32 v233, s59, v201
	v_add_u32_e32 v230, v233, v175
	v_add_u32_e32 v234, v233, v174
	ds_read_b128 v[202:205], v230 offset:32768
	ds_read_b128 v[206:209], v230 offset:36864
	ds_read_b128 v[210:213], v234
	v_mfma_f32_32x32x16_bf16 v[114:129], v[240:243], v[248:251], v[114:129]
	s_add_i32 s66, s60, 0x8000
	v_lshl_add_u64 v[226:227], v[160:161], 0, s[2:3]
	v_lshl_add_u64 v[228:229], v[144:145], 0, s[2:3]
	v_cndmask_b32_e32 v227, v229, v227, vcc
	v_cndmask_b32_e32 v226, v228, v226, vcc
	v_lshl_add_u64 v[226:227], v[0:1], 1, v[226:227]
	v_mfma_f32_32x32x16_bf16 v[98:113], v[244:247], v[248:251], v[98:113]
	s_add_i32 m0, s60, s62
	v_lshl_add_u64 v[228:229], v[142:143], 0, s[2:3]
	global_load_lds_dwordx4 v[226:227], off
	v_lshl_add_u64 v[226:227], v[158:159], 0, s[2:3]
	v_cndmask_b32_e32 v227, v229, v227, vcc
	v_cndmask_b32_e32 v226, v228, v226, vcc
	v_mfma_f32_32x32x16_bf16 v[82:97], v[240:243], v[214:217], v[82:97]
	v_lshl_add_u64 v[226:227], v[130:131], 1, v[226:227]
	s_add_i32 m0, s60, s63
	v_lshl_add_u64 v[228:229], v[140:141], 0, s[2:3]
	global_load_lds_dwordx4 v[226:227], off
	v_lshl_add_u64 v[226:227], v[156:157], 0, s[2:3]
	v_cndmask_b32_e32 v227, v229, v227, vcc
	v_mfma_f32_32x32x16_bf16 v[66:81], v[244:247], v[214:217], v[66:81]
	ds_read_b128 v[214:217], v234 offset:4096
	v_cndmask_b32_e32 v226, v228, v226, vcc
	v_lshl_add_u64 v[226:227], v[132:133], 1, v[226:227]
	s_add_i32 m0, s60, s64
	v_lshl_add_u64 v[228:229], v[138:139], 0, s[2:3]
	global_load_lds_dwordx4 v[226:227], off
	v_lshl_add_u64 v[226:227], v[154:155], 0, s[2:3]
	v_mfma_f32_32x32x16_bf16 v[50:65], v[240:243], v[218:221], v[50:65]
	v_cndmask_b32_e32 v226, v228, v226, vcc
	v_cndmask_b32_e32 v227, v229, v227, vcc
	s_add_i32 m0, s60, s65
	v_lshl_add_u64 v[226:227], v[134:135], 1, v[226:227]
	global_load_lds_dwordx4 v[226:227], off
	s_add_i32 m0, s66, s62
	v_mfma_f32_32x32x16_bf16 v[34:49], v[244:247], v[218:221], v[34:49]
	ds_read_b128 v[218:221], v234 offset:8192
	v_lshl_add_u64 v[226:227], v[146:147], 0, s[2:3]
	global_load_lds_dwordx4 v[226:227], off
	s_add_i32 m0, s66, s63
	v_lshl_add_u64 v[226:227], v[148:149], 0, s[2:3]
	global_load_lds_dwordx4 v[226:227], off
	s_add_i32 m0, s66, s64
	v_mfma_f32_32x32x16_bf16 v[18:33], v[240:243], v[222:225], v[18:33]
	v_lshl_add_u64 v[226:227], v[150:151], 0, s[2:3]
	global_load_lds_dwordx4 v[226:227], off
	v_lshl_add_u64 v[226:227], v[152:153], 0, s[2:3]
	s_add_i32 m0, s66, s65
	s_add_i32 s58, s59, 0
	global_load_lds_dwordx4 v[226:227], off
	v_mfma_f32_32x32x16_bf16 v[2:17], v[244:247], v[222:225], v[2:17]
	ds_read_b128 v[222:225], v234 offset:12288
	s_branch .Lgemm_rot_1274
.Lgemm_exit_1274:
	v_readlane_b32 s62, v255, 0
	v_readlane_b32 s63, v255, 1
	v_readlane_b32 s64, v255, 2
	v_readlane_b32 s65, v255, 3
	v_readlane_b32 s66, v255, 4
	v_mfma_f32_32x32x16_bf16 v[114:129], v[240:243], v[248:251], v[114:129]
	v_mfma_f32_32x32x16_bf16 v[98:113], v[244:247], v[248:251], v[98:113]
	v_mfma_f32_32x32x16_bf16 v[82:97], v[240:243], v[214:217], v[82:97]
	v_mfma_f32_32x32x16_bf16 v[66:81], v[244:247], v[214:217], v[66:81]
	v_mfma_f32_32x32x16_bf16 v[50:65], v[240:243], v[218:221], v[50:65]
	v_mfma_f32_32x32x16_bf16 v[34:49], v[244:247], v[218:221], v[34:49]
	v_mfma_f32_32x32x16_bf16 v[18:33], v[240:243], v[222:225], v[18:33]
	v_mfma_f32_32x32x16_bf16 v[2:17], v[244:247], v[222:225], v[2:17]
	s_add_i32 s15, s15, s10
	s_cmp_gt_u32 s15, 63
	s_cselect_b64 s[58:59], -1, 0
	s_and_b64 vcc, exec, s[58:59]
	s_cbranch_vccnz .LBB0_1277
	s_lshr_b32 s2, s15, 2
	s_and_b32 s2, s2, 0xffffff8
	s_and_b32 s3, s15, 7
	s_or_b32 s3, s2, s3
	s_lshl_b32 s2, s2, 7
	s_lshl_b32 s56, s15, 5
	s_sub_i32 s2, s56, s2
	s_lshl_b32 s3, s3, 11
	s_and_b32 s2, s2, 0xffffff00
	s_or_b32 s3, s3, s71
	v_add_u32_e32 v144, s2, v173
	v_lshlrev_b64 v[130:131], 1, v[130:131]
	v_mov_b64_e32 v[142:143], s[46:47]
	v_lshlrev_b64 v[132:133], 1, v[132:133]
	v_add_u32_e32 v0, s3, v163
	v_add_u32_e32 v148, s3, v168
	v_add_u32_e32 v149, s3, v171
	v_add_u32_e32 v150, s3, v173
	v_add_u32_e32 v151, s2, v163
	v_add_u32_e32 v146, s2, v168
	v_add_u32_e32 v147, s2, v171
	v_lshl_add_u64 v[138:139], s[42:43], 0, v[130:131]
	v_lshlrev_b64 v[134:135], 1, v[134:135]
	v_lshl_add_u64 v[130:131], s[46:47], 0, v[130:131]
	v_mad_i64_i32 v[142:143], s[2:3], v144, s96, v[142:143]
	v_lshl_add_u64 v[144:145], s[46:47], 0, v[132:133]
	v_lshl_add_u64 v[140:141], s[42:43], 0, v[134:135]
	v_mad_i64_i32 v[144:145], s[2:3], v147, s96, v[144:145]
	v_mad_i64_i32 v[130:131], s[2:3], v146, s96, v[130:131]
	v_lshl_add_u64 v[146:147], s[46:47], 0, v[136:137]
	v_lshl_add_u64 v[132:133], s[42:43], 0, v[132:133]
	v_lshl_add_u64 v[136:137], s[42:43], 0, v[136:137]
	v_mad_i64_i32 v[146:147], s[2:3], v151, s96, v[146:147]
	v_mad_i64_i32 v[140:141], s[2:3], v150, s29, v[140:141]
	v_mad_i64_i32 v[132:133], s[2:3], v149, s29, v[132:133]
	v_mad_i64_i32 v[138:139], s[2:3], v148, s29, v[138:139]
	v_mad_i64_i32 v[136:137], s[2:3], v0, s29, v[136:137]
	v_add3_u32 v0, 0, v177, v178
	s_nop 0
	v_readfirstlane_b32 s2, v0
	s_mov_b32 m0, s2
	v_add_u32_e32 v0, 0x8000, v0
	global_load_lds_dwordx4 v[136:137], off
	v_add3_u32 v136, 0, v169, v178
	v_add3_u32 v137, 0, v170, v178
	v_readfirstlane_b32 s2, v136
	s_mov_b32 m0, s2
	v_readfirstlane_b32 s2, v137
	global_load_lds_dwordx4 v[138:139], off
	s_mov_b32 m0, s2
	s_nop 0
	global_load_lds_dwordx4 v[132:133], off
	v_add3_u32 v132, 0, v172, v178
	s_nop 0
	v_readfirstlane_b32 s2, v132
	s_mov_b32 m0, s2
	v_readfirstlane_b32 s2, v0
	v_add_u32_e32 v0, 0x8000, v136
	global_load_lds_dwordx4 v[140:141], off
	s_mov_b32 m0, s2
	v_readfirstlane_b32 s2, v0
	v_add_u32_e32 v0, 0x8000, v137
	global_load_lds_dwordx4 v[146:147], off
	s_mov_b32 m0, s2
	v_readfirstlane_b32 s2, v0
	v_add_u32_e32 v0, 0x8000, v132
	global_load_lds_dwordx4 v[130:131], off
	s_mov_b32 m0, s2
	v_readfirstlane_b32 s2, v0
	global_load_lds_dwordx4 v[144:145], off
	v_lshl_add_u64 v[130:131], v[142:143], 0, v[134:135]
	s_mov_b32 m0, s2
	s_nop 0
	global_load_lds_dwordx4 v[130:131], off

; #define MFMA(a, b, c) __builtin_amdgcn_mfma_f32_32x32x16_bf16((a), (b), (c), 0, 0, 0)
;     ...
;     auto issue_at = [&](int mm0, int nn0, int kt, int buf) {
;       char* lb = L0 + buf * BUFB;
; #pragma unroll
;       for (int i = 0; i < 4; ++i) {
;         const int seg = wv * 4 + i, row = seg * 8 + gl_row;
;         const int c = (lane & 7) ^ ((row >> 1) & 7);
;         const u16* ap = (kt < g.split) ? g.a0 + (size_t)(mm0 + row) * g.ld0 + kt * g.ks0 : g.a1 + (size_t)(mm0 + row) * g.ld1 + (kt - g.split) * 64;
;         __builtin_amdgcn_global_load_lds((const unsigned*)(ap + c * 8), (__attribute__((address_space(3))) unsigned*)(lb + seg * 1024 + lane * 16), 16, 0, 0);
;       }
; #pragma unroll
;       for (int i = 0; i < BN / 64; ++i) {
;         const int seg = wv * (BN / 64) + i, row = seg * 8 + gl_row;
;         const int c = (lane & 7) ^ ((row >> 1) & 7);
;         __builtin_amdgcn_global_load_lds((const unsigned*)(g.W + (size_t)(nn0 + row) * g.K + kt * 64 + c * 8),
;                                          (__attribute__((address_space(3))) unsigned*)(lb + 256 * 128 + seg * 1024 + lane * 16), 16, 0, 0);
;       }
;     };
;     auto issue = [&](int kt, int buf) { issue_at(m0, n0, kt, buf); };
;     auto compute2 = [&](int buf) {
;       const char* lb = L0 + buf * BUFB;
; #pragma unroll
;       for (int ks = 0; ks < 4; ++ks) {
;         const int c = ks * 2 + hh;
;         bf16x8 wf[2], xf[MI];
; #pragma unroll
;         for (int j = 0; j < 2; ++j) { const int r = wn * 64 + j * 32 + l32; wf[j] = *(const bf16x8*)(lb + 256 * 128 + r * 128 + ((c ^ ((r >> 1) & 7)) << 4)); }
; #pragma unroll
;         for (int i = 0; i < MI; ++i) { const int r = wm * (MI * 32) + i * 32 + l32; xf[i] = *(const bf16x8*)(lb + r * 128 + ((c ^ ((r >> 1) & 7)) << 4)); }
; #pragma unroll
;         for (int i = 0; i < MI; ++i) {
;           acc[i][0] = MFMA(wf[0], xf[i], acc[i][0]);
;           acc[i][1] = MFMA(wf[1], xf[i], acc[i][1]);
;         }
;       }
;     };
.LBB0_1371:
	s_waitcnt vmcnt(16)
	s_barrier
	v_writelane_b32 v255, s60, 0
	v_writelane_b32 v255, s61, 1
	v_writelane_b32 v255, s62, 2
	v_writelane_b32 v255, s63, 3
	v_writelane_b32 v255, s64, 4
	v_add_u32_e32 v0, v167, v168
	v_add_u32_e32 v175, v157, v168
	v_add_u32_e32 v178, v159, v168
	v_add_u32_e32 v199, v165, v168
	s_nop 0
	v_readfirstlane_b32 s60, v0
	v_readfirstlane_b32 s61, v175
	v_readfirstlane_b32 s62, v178
	v_readfirstlane_b32 s63, v199
	s_and_b32 s17, s16, 0x10000
	s_xor_b32 s43, s17, 0x10000
	s_add_i32 s43, s43, 0
	s_add_i32 s17, s17, 0
	v_add_u32_e32 v0, s17, v174
	v_add_u32_e32 v175, v0, v170
	v_add_u32_e32 v0, v0, v169
	ds_read_b128 v[200:203], v175 offset:32768
	ds_read_b128 v[204:207], v175 offset:36864
	ds_read_b128 v[208:211], v0
	ds_read_b128 v[212:215], v0 offset:4096
	ds_read_b128 v[216:219], v0 offset:8192
	ds_read_b128 v[220:223], v0 offset:12288
	s_add_i32 s64, s43, 0x8000
	s_add_i32 m0, s43, s60
	v_lshl_add_u64 v[176:177], v[152:153], 0, s[10:11]
	global_load_lds_dwordx4 v[176:177], off
	s_add_i32 m0, s43, s61
	v_lshl_add_u64 v[176:177], v[150:151], 0, s[10:11]
	global_load_lds_dwordx4 v[176:177], off
	s_add_i32 m0, s43, s62
	v_lshl_add_u64 v[176:177], v[148:149], 0, s[10:11]
	global_load_lds_dwordx4 v[176:177], off
	s_add_i32 m0, s43, s63
	v_lshl_add_u64 v[176:177], v[146:147], 0, s[10:11]
	global_load_lds_dwordx4 v[176:177], off
	s_add_i32 m0, s64, s60
	v_lshl_add_u64 v[176:177], v[144:145], 0, s[10:11]
	global_load_lds_dwordx4 v[176:177], off
	s_add_i32 m0, s64, s61
	v_lshl_add_u64 v[176:177], v[142:143], 0, s[10:11]
	global_load_lds_dwordx4 v[176:177], off
	s_add_i32 m0, s64, s62
	v_lshl_add_u64 v[176:177], v[140:141], 0, s[10:11]
	global_load_lds_dwordx4 v[176:177], off
	s_add_i32 m0, s64, s63
	v_lshl_add_u64 v[176:177], v[138:139], 0, s[10:11]
	global_load_lds_dwordx4 v[176:177], off
.Lgemm_rot_1371:
	v_add_u32_e32 v0, s17, v173
	v_add_u32_e32 v175, v0, v170
	v_add_u32_e32 v0, v0, v169
	s_waitcnt lgkmcnt(3)
	v_mfma_f32_32x32x16_bf16 v[114:129], v[200:203], v[208:211], v[114:129]
	s_add_i32 s16, s16, 0x10000
	s_add_u32 s10, s10, 0x80
	s_addc_u32 s11, s11, 0
	s_cmpk_eq_i32 s10, 0x780
	ds_read_b128 v[224:227], v175 offset:32768
	v_mfma_f32_32x32x16_bf16 v[98:113], v[204:207], v[208:211], v[98:113]
	ds_read_b128 v[228:231], v175 offset:36864
	s_waitcnt lgkmcnt(4)
	v_mfma_f32_32x32x16_bf16 v[82:97], v[200:203], v[212:215], v[82:97]
	ds_read_b128 v[232:235], v0
	v_mfma_f32_32x32x16_bf16 v[66:81], v[204:207], v[212:215], v[66:81]
	ds_read_b128 v[240:243], v0 offset:4096
	s_waitcnt lgkmcnt(5)
	v_mfma_f32_32x32x16_bf16 v[50:65], v[200:203], v[216:219], v[50:65]
	ds_read_b128 v[244:247], v0 offset:8192
	v_mfma_f32_32x32x16_bf16 v[34:49], v[204:207], v[216:219], v[34:49]
	ds_read_b128 v[248:251], v0 offset:12288
	s_waitcnt lgkmcnt(6)
	v_mfma_f32_32x32x16_bf16 v[18:33], v[200:203], v[220:223], v[18:33]
	v_mfma_f32_32x32x16_bf16 v[2:17], v[204:207], v[220:223], v[2:17]
	v_add_u32_e32 v0, s17, v172
	v_add_u32_e32 v175, v0, v170
	v_add_u32_e32 v0, v0, v169
	s_waitcnt lgkmcnt(3)
	v_mfma_f32_32x32x16_bf16 v[114:129], v[224:227], v[232:235], v[114:129]
	ds_read_b128 v[200:203], v175 offset:32768
	v_mfma_f32_32x32x16_bf16 v[98:113], v[228:231], v[232:235], v[98:113]
	ds_read_b128 v[204:207], v175 offset:36864
	s_waitcnt lgkmcnt(4)
	v_mfma_f32_32x32x16_bf16 v[82:97], v[224:227], v[240:243], v[82:97]
	ds_read_b128 v[208:211], v0
	v_mfma_f32_32x32x16_bf16 v[66:81], v[228:231], v[240:243], v[66:81]
	ds_read_b128 v[212:215], v0 offset:4096
	s_waitcnt lgkmcnt(5)
	v_mfma_f32_32x32x16_bf16 v[50:65], v[224:227], v[244:247], v[50:65]
	ds_read_b128 v[216:219], v0 offset:8192
	v_mfma_f32_32x32x16_bf16 v[34:49], v[228:231], v[244:247], v[34:49]
	ds_read_b128 v[220:223], v0 offset:12288
	s_waitcnt lgkmcnt(6)
	v_mfma_f32_32x32x16_bf16 v[18:33], v[224:227], v[248:251], v[18:33]
	v_mfma_f32_32x32x16_bf16 v[2:17], v[228:231], v[248:251], v[2:17]
	v_add_u32_e32 v0, s17, v171
	v_add_u32_e32 v175, v0, v170
	v_add_u32_e32 v0, v0, v169
	s_waitcnt lgkmcnt(3)
	v_mfma_f32_32x32x16_bf16 v[114:129], v[200:203], v[208:211], v[114:129]
	ds_read_b128 v[224:227], v175 offset:32768
	v_mfma_f32_32x32x16_bf16 v[98:113], v[204:207], v[208:211], v[98:113]
	ds_read_b128 v[228:231], v175 offset:36864
	s_waitcnt lgkmcnt(4)
	v_mfma_f32_32x32x16_bf16 v[82:97], v[200:203], v[212:215], v[82:97]
	ds_read_b128 v[232:235], v0
	v_mfma_f32_32x32x16_bf16 v[66:81], v[204:207], v[212:215], v[66:81]
	ds_read_b128 v[240:243], v0 offset:4096
	s_waitcnt lgkmcnt(5)
	v_mfma_f32_32x32x16_bf16 v[50:65], v[200:203], v[216:219], v[50:65]
	ds_read_b128 v[244:247], v0 offset:8192
	v_mfma_f32_32x32x16_bf16 v[34:49], v[204:207], v[216:219], v[34:49]
	ds_read_b128 v[248:251], v0 offset:12288
	s_waitcnt lgkmcnt(6)
	v_mfma_f32_32x32x16_bf16 v[18:33], v[200:203], v[220:223], v[18:33]
	v_mfma_f32_32x32x16_bf16 v[2:17], v[204:207], v[220:223], v[2:17]
	s_waitcnt vmcnt(0)
	s_waitcnt vmcnt(0) lgkmcnt(0)
	s_barrier
	s_cbranch_scc1 .Lgemm_exit_1371
	s_and_b32 s17, s16, 0x10000
	s_xor_b32 s43, s17, 0x10000
	s_add_i32 s43, s43, 0
	s_add_i32 s17, s17, 0
	v_add_u32_e32 v0, s17, v174
	v_add_u32_e32 v175, v0, v170
	v_add_u32_e32 v0, v0, v169
	ds_read_b128 v[200:203], v175 offset:32768
	ds_read_b128 v[204:207], v175 offset:36864
	ds_read_b128 v[208:211], v0
	ds_read_b128 v[212:215], v0 offset:4096
	ds_read_b128 v[216:219], v0 offset:8192
	ds_read_b128 v[220:223], v0 offset:12288
	v_mfma_f32_32x32x16_bf16 v[114:129], v[224:227], v[232:235], v[114:129]
	s_add_i32 s64, s43, 0x8000
	s_add_i32 m0, s43, s60
	v_lshl_add_u64 v[176:177], v[152:153], 0, s[10:11]
	global_load_lds_dwordx4 v[176:177], off
	v_mfma_f32_32x32x16_bf16 v[98:113], v[228:231], v[232:235], v[98:113]
	s_add_i32 m0, s43, s61
	v_lshl_add_u64 v[176:177], v[150:151], 0, s[10:11]
	global_load_lds_dwordx4 v[176:177], off
	s_add_i32 m0, s43, s62
	v_mfma_f32_32x32x16_bf16 v[82:97], v[224:227], v[240:243], v[82:97]
	v_lshl_add_u64 v[176:177], v[148:149], 0, s[10:11]
	global_load_lds_dwordx4 v[176:177], off
	s_add_i32 m0, s43, s63
	v_lshl_add_u64 v[176:177], v[146:147], 0, s[10:11]
	v_mfma_f32_32x32x16_bf16 v[66:81], v[228:231], v[240:243], v[66:81]
	global_load_lds_dwordx4 v[176:177], off
	s_add_i32 m0, s64, s60
	v_lshl_add_u64 v[176:177], v[144:145], 0, s[10:11]
	global_load_lds_dwordx4 v[176:177], off
	v_mfma_f32_32x32x16_bf16 v[50:65], v[224:227], v[244:247], v[50:65]
	s_add_i32 m0, s64, s61
	v_lshl_add_u64 v[176:177], v[142:143], 0, s[10:11]
	global_load_lds_dwordx4 v[176:177], off
	s_add_i32 m0, s64, s62
	v_mfma_f32_32x32x16_bf16 v[34:49], v[228:231], v[244:247], v[34:49]
	v_lshl_add_u64 v[176:177], v[140:141], 0, s[10:11]
	global_load_lds_dwordx4 v[176:177], off
	s_add_i32 m0, s64, s63
	v_lshl_add_u64 v[176:177], v[138:139], 0, s[10:11]
	v_mfma_f32_32x32x16_bf16 v[18:33], v[224:227], v[248:251], v[18:33]
	global_load_lds_dwordx4 v[176:177], off
	v_mfma_f32_32x32x16_bf16 v[2:17], v[228:231], v[248:251], v[2:17]
	s_branch .Lgemm_rot_1371
;     ...
;     auto issue_at = [&](int mm0, int nn0, int kt, int buf) {
;       char* lb = L0 + buf * BUFB;
; #pragma unroll
;       for (int i = 0; i < 4; ++i) {
;         const int seg = wv * 4 + i, row = seg * 8 + gl_row;
;         const int c = (lane & 7) ^ ((row >> 1) & 7);
;         const u16* ap = (kt < g.split) ? g.a0 + (size_t)(mm0 + row) * g.ld0 + kt * g.ks0 : g.a1 + (size_t)(mm0 + row) * g.ld1 + (kt - g.split) * 64;
;         __builtin_amdgcn_global_load_lds((const unsigned*)(ap + c * 8), (__attribute__((address_space(3))) unsigned*)(lb + seg * 1024 + lane * 16), 16, 0, 0);
;       }
; #pragma unroll
;       for (int i = 0; i < BN / 64; ++i) {
;         const int seg = wv * (BN / 64) + i, row = seg * 8 + gl_row;
;         const int c = (lane & 7) ^ ((row >> 1) & 7);
;         __builtin_amdgcn_global_load_lds((const unsigned*)(g.W + (size_t)(nn0 + row) * g.K + kt * 64 + c * 8),
;                                          (__attribute__((address_space(3))) unsigned*)(lb + 256 * 128 + seg * 1024 + lane * 16), 16, 0, 0);
;       }
;     };
; template <int MODE, int EPI, int BN>
; DI void gemm_phase(CP p, const GArgs& g, int NT, char* smem) {
;     ...
;   for (int e = j; e < total; e += nj) {
;     const int grp = e / (8 * NT);
;     const int rem = e - grp * 8 * NT;
;     const int e2 = e + nj;
;     const bool has_next = can_chain && e2 < total;
;     const int grp2 = e2 / (8 * NT), rem2 = e2 - grp2 * 8 * NT;
;     const int chain = can_chain ? ((first ? 0 : 1) | (has_next ? 2 : 0)) : 0;
;     gemm_tile<MODE, EPI, BN>(p, g, x + 8 * (grp * 8 + (rem & 7)), rem >> 3, smem, chain, x + 8 * (grp2 * 8 + (rem2 & 7)), rem2 >> 3);
;     first = false;
;   }
.Lgemm_exit_1371:
	v_readlane_b32 s60, v255, 0
	v_readlane_b32 s61, v255, 1
	v_readlane_b32 s62, v255, 2
	v_readlane_b32 s63, v255, 3
	v_readlane_b32 s64, v255, 4
	v_mfma_f32_32x32x16_bf16 v[114:129], v[224:227], v[232:235], v[114:129]
	v_mfma_f32_32x32x16_bf16 v[98:113], v[228:231], v[232:235], v[98:113]
	v_mfma_f32_32x32x16_bf16 v[82:97], v[224:227], v[240:243], v[82:97]
	v_mfma_f32_32x32x16_bf16 v[66:81], v[228:231], v[240:243], v[66:81]
	v_mfma_f32_32x32x16_bf16 v[50:65], v[224:227], v[244:247], v[50:65]
	v_mfma_f32_32x32x16_bf16 v[34:49], v[228:231], v[244:247], v[34:49]
	v_mfma_f32_32x32x16_bf16 v[18:33], v[224:227], v[248:251], v[18:33]
	v_mfma_f32_32x32x16_bf16 v[2:17], v[228:231], v[248:251], v[2:17]
	s_add_i32 s51, s51, s50
	s_cmpk_gt_u32 s51, 0x15f
	s_cselect_b64 s[10:11], -1, 0
	s_and_b64 vcc, exec, s[10:11]
	s_cbranch_vccnz .LBB0_1374
	s_mul_hi_u32 s16, s51, 0xba2e8ba3
	s_lshr_b32 s16, s16, 7
	s_mul_i32 s17, s16, 0xffffff50
	s_lshl_b32 s43, s51, 3
	s_add_i32 s17, s17, s51
	s_lshl_b32 s16, s16, 6
	s_and_b32 s43, s43, 56
	s_or_b32 s16, s16, s43
	s_lshl_b32 s17, s17, 5
	s_or_b32 s16, s16, s72
	s_and_b32 s17, s17, 0xffffff00
	s_lshl_b32 s16, s16, 8
	v_add_u32_e32 v148, s17, v158
	v_add_u32_e32 v138, s16, v156
	v_ashrrev_i32_e32 v149, 31, v148
	v_ashrrev_i32_e32 v139, 31, v138
	v_lshl_add_u64 v[176:177], s[46:47], 0, v[136:137]
	v_lshl_add_u64 v[136:137], s[48:49], 0, v[136:137]
	v_lshlrev_b64 v[148:149], 11, v[148:149]
	v_add3_u32 v0, 0, v167, v168
	v_add_u32_e32 v140, s16, v158
	v_add_u32_e32 v142, s16, v164
	v_add_u32_e32 v144, s16, v166
	v_lshlrev_b64 v[138:139], 11, v[138:139]
	v_lshl_add_u64 v[136:137], v[136:137], 0, v[148:149]
	v_lshl_add_u64 v[148:149], s[48:49], 0, v[134:135]
	v_lshl_add_u64 v[134:135], s[46:47], 0, v[134:135]
	v_readfirstlane_b32 s16, v0
	v_lshl_add_u64 v[134:135], v[134:135], 0, v[138:139]
	s_mov_b32 m0, s16
	v_ashrrev_i32_e32 v141, 31, v140
	global_load_lds_dwordx4 v[134:135], off
	v_add3_u32 v134, 0, v157, v168
	v_ashrrev_i32_e32 v143, 31, v142
	v_lshlrev_b64 v[140:141], 11, v[140:141]
	v_readfirstlane_b32 s16, v134
	v_add3_u32 v135, 0, v159, v168
	v_lshlrev_b64 v[142:143], 11, v[142:143]
	v_lshl_add_u64 v[202:203], s[48:49], 0, v[132:133]
	v_lshl_add_u64 v[132:133], s[46:47], 0, v[132:133]
	v_lshl_add_u64 v[140:141], v[176:177], 0, v[140:141]
	s_mov_b32 m0, s16
	v_readfirstlane_b32 s16, v135
	v_lshl_add_u64 v[132:133], v[132:133], 0, v[142:143]
	global_load_lds_dwordx4 v[140:141], off
	s_mov_b32 m0, s16
	v_ashrrev_i32_e32 v145, 31, v144
	v_add_u32_e32 v146, s17, v156
	global_load_lds_dwordx4 v[132:133], off
	v_add3_u32 v132, 0, v165, v168
	v_ashrrev_i32_e32 v147, 31, v146
	v_lshl_add_u64 v[200:201], s[46:47], 0, v[130:131]
	v_lshlrev_b64 v[144:145], 11, v[144:145]
	v_readfirstlane_b32 s16, v132
	v_add_u32_e32 v0, 0x8000, v0
	v_add_u32_e32 v150, s17, v164
	v_add_u32_e32 v152, s17, v166
	v_lshlrev_b64 v[146:147], 11, v[146:147]
	v_lshl_add_u64 v[144:145], v[200:201], 0, v[144:145]
	s_mov_b32 m0, s16
	v_readfirstlane_b32 s16, v0
	v_add_u32_e32 v0, 0x8000, v134
	v_ashrrev_i32_e32 v151, 31, v150
	v_ashrrev_i32_e32 v153, 31, v152
	v_lshl_add_u64 v[146:147], v[148:149], 0, v[146:147]
	global_load_lds_dwordx4 v[144:145], off
	s_mov_b32 m0, s16
	v_readfirstlane_b32 s16, v0
	v_add_u32_e32 v0, 0x8000, v135
	v_lshlrev_b64 v[150:151], 11, v[150:151]
	v_lshlrev_b64 v[152:153], 11, v[152:153]
	global_load_lds_dwordx4 v[146:147], off
	s_mov_b32 m0, s16
	v_readfirstlane_b32 s16, v0
	v_add_u32_e32 v0, 0x8000, v132
	v_lshl_add_u64 v[152:153], s[48:49], 0, v[152:153]
	v_lshl_add_u64 v[150:151], v[202:203], 0, v[150:151]
	global_load_lds_dwordx4 v[136:137], off
	s_mov_b32 m0, s16
	v_readfirstlane_b32 s16, v0
	global_load_lds_dwordx4 v[150:151], off
	v_lshl_add_u64 v[130:131], v[152:153], 0, v[130:131]
	s_mov_b32 m0, s16
	s_nop 0
	global_load_lds_dwordx4 v[130:131], off
